# grid barrier: first arriving workgroup of each XCD starts an early L2 write-back
# baseline (speedup 1.0000x reference)
; __device__ __forceinline__ unsigned xb_ld(unsigned* p)              { return __hip_atomic_load(p, __ATOMIC_RELAXED, __HIP_MEMORY_SCOPE_AGENT); }
; __device__ __forceinline__ unsigned xb_add(unsigned* p, unsigned v) { return __hip_atomic_fetch_add(p, v, __ATOMIC_RELAXED, __HIP_MEMORY_SCOPE_AGENT); }
; #define XB_SPIN(cond, bar) do { unsigned _sp = 0; while (cond) { __builtin_amdgcn_s_sleep(1); \
;     if ((++_sp & 255u) == 0u) { if (xb_ld(&(bar)[XB_TMO])) break; if (_sp > XB_SPIN_CAP) { atomicAdd(&(bar)[XB_TMO], 1u); break; } } } } while (0)
; __device__ __forceinline__ void xcd_barrier(const XcdBarrier& b) {
;     asm volatile("s_waitcnt vmcnt(0)" ::: "memory");
;     __syncthreads();
;     if (threadIdx.x == 0) {
;         unsigned* bar = b.bar;
;         __builtin_amdgcn_s_waitcnt(0);
;         unsigned nloc = b.st[0], nx = b.st[1];
;         if (nloc == 0u) { xcd_barrier_complete(bar, b.x, nloc, nx); b.st[0] = nloc; b.st[1] = nx; }
;         const unsigned old = xb_add(&bar[XB_XSUB(b.x)], 1u);
;         const unsigned gen = old / nloc;
;         if (old + 1u == (gen + 1u) * nloc) {
;             __builtin_amdgcn_fence(__ATOMIC_RELEASE, "agent");
;             asm volatile("s_waitcnt vmcnt(0)" ::: "memory");
;             const unsigned og = xb_add(&bar[XB_TOP], 1u);
;             const unsigned tg = og / nx;
;             if (og + 1u == (tg + 1u) * nx) xb_add(&bar[XB_TOPGEN], 1u);
;             else XB_SPIN(xb_ld(&bar[XB_TOPGEN]) == tg, bar);
;             __builtin_amdgcn_fence(__ATOMIC_ACQUIRE, "agent");
;             xb_add(&bar[XB_XGEN(b.x)], 1u);
;             asm volatile("s_waitcnt vmcnt(0)" ::: "memory");
;         } else {
;             XB_SPIN(xb_ld(&bar[XB_XGEN(b.x)]) == gen, bar);
;             __builtin_amdgcn_fence(__ATOMIC_ACQUIRE, "agent");
.LBB0_58:
	s_or_b64 exec, exec, s[28:29]
	v_cvt_f32_u32_e32 v4, v2
	s_waitcnt vmcnt(0)
	v_readfirstlane_b32 s6, v3
	v_sub_u32_e32 v3, 0, v2
	v_rcp_iflag_f32_e32 v4, v4
	v_add_u32_e32 v5, s6, v1
	v_mul_u32_u24_e32 v250, 0, v2
	v_cmp_ne_u32_e64 s[28:29], v250, v5
	s_nop 3
	s_and_b64 s[28:29], s[28:29], exec
	s_cbranch_scc1 .Lfa_skip_0
	buffer_wbl2 sc1
.Lfa_skip_0:
	v_mul_f32_e32 v4, 0x4f7ffffe, v4
	v_cvt_u32_f32_e32 v4, v4
	v_mul_lo_u32 v1, v3, v4
	v_mul_hi_u32 v1, v4, v1
	v_add_u32_e32 v1, v4, v1
	v_mul_hi_u32 v1, v5, v1
	v_mul_lo_u32 v3, v1, v2
	v_sub_u32_e32 v3, v5, v3
	v_add_u32_e32 v4, 1, v1
	v_cmp_ge_u32_e32 vcc, v3, v2
	s_nop 1
	v_cndmask_b32_e32 v1, v1, v4, vcc
	v_sub_u32_e32 v4, v3, v2
	v_cndmask_b32_e32 v3, v3, v4, vcc
	v_add_u32_e32 v4, 1, v1
	v_cmp_ge_u32_e32 vcc, v3, v2
	v_add_u32_e32 v3, 1, v5
	s_nop 0
	v_cndmask_b32_e32 v1, v1, v4, vcc
	v_mul_lo_u32 v4, v2, v1
	v_add_u32_e32 v2, v4, v2
	v_cmp_ne_u32_e32 vcc, v3, v2
	s_and_saveexec_b64 s[6:7], vcc
	s_xor_b64 s[6:7], exec, s[6:7]
	s_cbranch_execz .LBB0_72
	s_waitcnt lgkmcnt(0)
	v_mov_b32_e32 v0, 0x2000
	global_load_dword v0, v0, s[30:31] offset:1024 sc1
	s_add_u32 s38, s30, 0x2400
	s_addc_u32 s39, s31, 0
	s_waitcnt vmcnt(0)
	v_cmp_eq_u32_e32 vcc, v0, v1
	s_and_saveexec_b64 s[34:35], vcc
	s_cbranch_execz .LBB0_71
	s_add_u32 s36, s72, 0x80200
	s_addc_u32 s37, s73, 0
	s_mov_b32 s8, 1
	s_mov_b64 s[50:51], 0
	v_mov_b32_e32 v0, 0
	s_branch .LBB0_62

; __device__ __forceinline__ unsigned xb_ld(unsigned* p)              { return __hip_atomic_load(p, __ATOMIC_RELAXED, __HIP_MEMORY_SCOPE_AGENT); }
; __device__ __forceinline__ unsigned xb_add(unsigned* p, unsigned v) { return __hip_atomic_fetch_add(p, v, __ATOMIC_RELAXED, __HIP_MEMORY_SCOPE_AGENT); }
; #define XB_SPIN(cond, bar) do { unsigned _sp = 0; while (cond) { __builtin_amdgcn_s_sleep(1); \
;     if ((++_sp & 255u) == 0u) { if (xb_ld(&(bar)[XB_TMO])) break; if (_sp > XB_SPIN_CAP) { atomicAdd(&(bar)[XB_TMO], 1u); break; } } } } while (0)
; __device__ __forceinline__ void xcd_barrier(const XcdBarrier& b) {
;     asm volatile("s_waitcnt vmcnt(0)" ::: "memory");
;     __syncthreads();
;     if (threadIdx.x == 0) {
;         unsigned* bar = b.bar;
;         __builtin_amdgcn_s_waitcnt(0);
;         unsigned nloc = b.st[0], nx = b.st[1];
;         if (nloc == 0u) { xcd_barrier_complete(bar, b.x, nloc, nx); b.st[0] = nloc; b.st[1] = nx; }
;         const unsigned old = xb_add(&bar[XB_XSUB(b.x)], 1u);
;         const unsigned gen = old / nloc;
;         if (old + 1u == (gen + 1u) * nloc) {
;             __builtin_amdgcn_fence(__ATOMIC_RELEASE, "agent");
;             asm volatile("s_waitcnt vmcnt(0)" ::: "memory");
;             const unsigned og = xb_add(&bar[XB_TOP], 1u);
;             const unsigned tg = og / nx;
;             if (og + 1u == (tg + 1u) * nx) xb_add(&bar[XB_TOPGEN], 1u);
;             else XB_SPIN(xb_ld(&bar[XB_TOPGEN]) == tg, bar);
;             __builtin_amdgcn_fence(__ATOMIC_ACQUIRE, "agent");
;             xb_add(&bar[XB_XGEN(b.x)], 1u);
;             asm volatile("s_waitcnt vmcnt(0)" ::: "memory");
;         } else {
;             XB_SPIN(xb_ld(&bar[XB_XGEN(b.x)]) == gen, bar);
;             __builtin_amdgcn_fence(__ATOMIC_ACQUIRE, "agent");
.LBB0_197:
	s_or_b64 exec, exec, s[28:29]
	v_cvt_f32_u32_e32 v4, v2
	s_waitcnt vmcnt(0)
	v_readfirstlane_b32 s6, v3
	v_sub_u32_e32 v3, 0, v2
	v_rcp_iflag_f32_e32 v4, v4
	v_add_u32_e32 v5, s6, v1
	v_mul_u32_u24_e32 v250, 1, v2
	v_cmp_ne_u32_e64 s[28:29], v250, v5
	s_nop 3
	s_and_b64 s[28:29], s[28:29], exec
	s_cbranch_scc1 .Lfa_skip_1
	buffer_wbl2 sc1
.Lfa_skip_1:
	v_mul_f32_e32 v4, 0x4f7ffffe, v4
	v_cvt_u32_f32_e32 v4, v4
	v_mul_lo_u32 v1, v3, v4
	v_mul_hi_u32 v1, v4, v1
	v_add_u32_e32 v1, v4, v1
	v_mul_hi_u32 v1, v5, v1
	v_mul_lo_u32 v3, v1, v2
	v_sub_u32_e32 v3, v5, v3
	v_add_u32_e32 v4, 1, v1
	v_cmp_ge_u32_e32 vcc, v3, v2
	s_nop 1
	v_cndmask_b32_e32 v1, v1, v4, vcc
	v_sub_u32_e32 v4, v3, v2
	v_cndmask_b32_e32 v3, v3, v4, vcc
	v_add_u32_e32 v4, 1, v1
	v_cmp_ge_u32_e32 vcc, v3, v2
	v_add_u32_e32 v3, 1, v5
	s_nop 0
	v_cndmask_b32_e32 v1, v1, v4, vcc
	v_mul_lo_u32 v4, v2, v1
	v_add_u32_e32 v2, v4, v2
	v_cmp_ne_u32_e32 vcc, v3, v2
	s_and_saveexec_b64 s[6:7], vcc
	s_xor_b64 s[6:7], exec, s[6:7]
	s_cbranch_execz .LBB0_211
	s_waitcnt lgkmcnt(0)
	v_mov_b32_e32 v0, 0x2000
	global_load_dword v0, v0, s[36:37] offset:1024 sc1
	s_add_u32 s62, s36, 0x2400
	s_addc_u32 s63, s37, 0
	s_waitcnt vmcnt(0)
	v_cmp_eq_u32_e32 vcc, v0, v1
	s_and_saveexec_b64 s[46:47], vcc
	s_cbranch_execz .LBB0_210
	s_add_u32 s50, s72, 0x80200
	s_addc_u32 s51, s73, 0
	s_mov_b32 s8, 1
	s_mov_b64 s[64:65], 0
	v_mov_b32_e32 v0, 0
	s_branch .LBB0_201

; __device__ __forceinline__ unsigned xb_ld(unsigned* p)              { return __hip_atomic_load(p, __ATOMIC_RELAXED, __HIP_MEMORY_SCOPE_AGENT); }
; __device__ __forceinline__ unsigned xb_add(unsigned* p, unsigned v) { return __hip_atomic_fetch_add(p, v, __ATOMIC_RELAXED, __HIP_MEMORY_SCOPE_AGENT); }
; #define XB_SPIN(cond, bar) do { unsigned _sp = 0; while (cond) { __builtin_amdgcn_s_sleep(1); \
;     if ((++_sp & 255u) == 0u) { if (xb_ld(&(bar)[XB_TMO])) break; if (_sp > XB_SPIN_CAP) { atomicAdd(&(bar)[XB_TMO], 1u); break; } } } } while (0)
; __device__ __forceinline__ void xcd_barrier(const XcdBarrier& b) {
;     asm volatile("s_waitcnt vmcnt(0)" ::: "memory");
;     __syncthreads();
;     if (threadIdx.x == 0) {
;         unsigned* bar = b.bar;
;         __builtin_amdgcn_s_waitcnt(0);
;         unsigned nloc = b.st[0], nx = b.st[1];
;         if (nloc == 0u) { xcd_barrier_complete(bar, b.x, nloc, nx); b.st[0] = nloc; b.st[1] = nx; }
;         const unsigned old = xb_add(&bar[XB_XSUB(b.x)], 1u);
;         const unsigned gen = old / nloc;
;         if (old + 1u == (gen + 1u) * nloc) {
;             __builtin_amdgcn_fence(__ATOMIC_RELEASE, "agent");
;             asm volatile("s_waitcnt vmcnt(0)" ::: "memory");
;             const unsigned og = xb_add(&bar[XB_TOP], 1u);
;             const unsigned tg = og / nx;
;             if (og + 1u == (tg + 1u) * nx) xb_add(&bar[XB_TOPGEN], 1u);
;             else XB_SPIN(xb_ld(&bar[XB_TOPGEN]) == tg, bar);
;             __builtin_amdgcn_fence(__ATOMIC_ACQUIRE, "agent");
;             xb_add(&bar[XB_XGEN(b.x)], 1u);
;             asm volatile("s_waitcnt vmcnt(0)" ::: "memory");
;         } else {
;             XB_SPIN(xb_ld(&bar[XB_XGEN(b.x)]) == gen, bar);
;             __builtin_amdgcn_fence(__ATOMIC_ACQUIRE, "agent");
.LBB0_332:
	s_or_b64 exec, exec, s[28:29]
	v_cvt_f32_u32_e32 v4, v2
	s_waitcnt vmcnt(0)
	v_readfirstlane_b32 s6, v3
	v_sub_u32_e32 v3, 0, v2
	v_rcp_iflag_f32_e32 v4, v4
	v_add_u32_e32 v5, s6, v1
	v_mul_u32_u24_e32 v250, 2, v2
	v_cmp_ne_u32_e64 s[28:29], v250, v5
	s_nop 3
	s_and_b64 s[28:29], s[28:29], exec
	s_cbranch_scc1 .Lfa_skip_2
	buffer_wbl2 sc1
.Lfa_skip_2:
	v_mul_f32_e32 v4, 0x4f7ffffe, v4
	v_cvt_u32_f32_e32 v4, v4
	v_mul_lo_u32 v1, v3, v4
	v_mul_hi_u32 v1, v4, v1
	v_add_u32_e32 v1, v4, v1
	v_mul_hi_u32 v1, v5, v1
	v_mul_lo_u32 v3, v1, v2
	v_sub_u32_e32 v3, v5, v3
	v_add_u32_e32 v4, 1, v1
	v_cmp_ge_u32_e32 vcc, v3, v2
	s_nop 1
	v_cndmask_b32_e32 v1, v1, v4, vcc
	v_sub_u32_e32 v4, v3, v2
	v_cndmask_b32_e32 v3, v3, v4, vcc
	v_add_u32_e32 v4, 1, v1
	v_cmp_ge_u32_e32 vcc, v3, v2
	v_add_u32_e32 v3, 1, v5
	s_nop 0
	v_cndmask_b32_e32 v1, v1, v4, vcc
	v_mul_lo_u32 v4, v2, v1
	v_add_u32_e32 v2, v4, v2
	v_cmp_ne_u32_e32 vcc, v3, v2
	s_and_saveexec_b64 s[6:7], vcc
	s_xor_b64 s[6:7], exec, s[6:7]
	s_cbranch_execz .LBB0_346
	s_waitcnt lgkmcnt(0)
	v_mov_b32_e32 v0, 0x2000
	global_load_dword v0, v0, s[40:41] offset:1024 sc1
	s_add_u32 s50, s40, 0x2400
	s_addc_u32 s51, s41, 0
	s_waitcnt vmcnt(0)
	v_cmp_eq_u32_e32 vcc, v0, v1
	s_and_saveexec_b64 s[42:43], vcc
	s_cbranch_execz .LBB0_345
	s_add_u32 s46, s72, 0x80200
	s_addc_u32 s47, s73, 0
	s_mov_b32 s8, 1
	s_mov_b64 s[52:53], 0
	v_mov_b32_e32 v0, 0
	s_branch .LBB0_336

; __device__ __forceinline__ unsigned xb_ld(unsigned* p)              { return __hip_atomic_load(p, __ATOMIC_RELAXED, __HIP_MEMORY_SCOPE_AGENT); }
; __device__ __forceinline__ unsigned xb_add(unsigned* p, unsigned v) { return __hip_atomic_fetch_add(p, v, __ATOMIC_RELAXED, __HIP_MEMORY_SCOPE_AGENT); }
; #define XB_SPIN(cond, bar) do { unsigned _sp = 0; while (cond) { __builtin_amdgcn_s_sleep(1); \
;     if ((++_sp & 255u) == 0u) { if (xb_ld(&(bar)[XB_TMO])) break; if (_sp > XB_SPIN_CAP) { atomicAdd(&(bar)[XB_TMO], 1u); break; } } } } while (0)
; __device__ __forceinline__ void xcd_barrier(const XcdBarrier& b) {
;     asm volatile("s_waitcnt vmcnt(0)" ::: "memory");
;     __syncthreads();
;     if (threadIdx.x == 0) {
;         unsigned* bar = b.bar;
;         __builtin_amdgcn_s_waitcnt(0);
;         unsigned nloc = b.st[0], nx = b.st[1];
;         if (nloc == 0u) { xcd_barrier_complete(bar, b.x, nloc, nx); b.st[0] = nloc; b.st[1] = nx; }
;         const unsigned old = xb_add(&bar[XB_XSUB(b.x)], 1u);
;         const unsigned gen = old / nloc;
;         if (old + 1u == (gen + 1u) * nloc) {
;             __builtin_amdgcn_fence(__ATOMIC_RELEASE, "agent");
;             asm volatile("s_waitcnt vmcnt(0)" ::: "memory");
;             const unsigned og = xb_add(&bar[XB_TOP], 1u);
;             const unsigned tg = og / nx;
;             if (og + 1u == (tg + 1u) * nx) xb_add(&bar[XB_TOPGEN], 1u);
;             else XB_SPIN(xb_ld(&bar[XB_TOPGEN]) == tg, bar);
;             __builtin_amdgcn_fence(__ATOMIC_ACQUIRE, "agent");
;             xb_add(&bar[XB_XGEN(b.x)], 1u);
;             asm volatile("s_waitcnt vmcnt(0)" ::: "memory");
;         } else {
;             XB_SPIN(xb_ld(&bar[XB_XGEN(b.x)]) == gen, bar);
;             __builtin_amdgcn_fence(__ATOMIC_ACQUIRE, "agent");
.LBB0_429:
	s_or_b64 exec, exec, s[6:7]
	v_cvt_f32_u32_e32 v4, v2
	s_waitcnt vmcnt(0)
	v_readfirstlane_b32 s4, v3
	v_sub_u32_e32 v3, 0, v2
	v_rcp_iflag_f32_e32 v4, v4
	v_add_u32_e32 v5, s4, v1
	v_mul_u32_u24_e32 v250, 3, v2
	v_cmp_ne_u32_e64 s[6:7], v250, v5
	s_nop 3
	s_and_b64 s[6:7], s[6:7], exec
	s_cbranch_scc1 .Lfa_skip_3
	buffer_wbl2 sc1
.Lfa_skip_3:
	v_mul_f32_e32 v4, 0x4f7ffffe, v4
	v_cvt_u32_f32_e32 v4, v4
	v_mul_lo_u32 v1, v3, v4
	v_mul_hi_u32 v1, v4, v1
	v_add_u32_e32 v1, v4, v1
	v_mul_hi_u32 v1, v5, v1
	v_mul_lo_u32 v3, v1, v2
	v_sub_u32_e32 v3, v5, v3
	v_add_u32_e32 v4, 1, v1
	v_cmp_ge_u32_e32 vcc, v3, v2
	s_nop 1
	v_cndmask_b32_e32 v1, v1, v4, vcc
	v_sub_u32_e32 v4, v3, v2
	v_cndmask_b32_e32 v3, v3, v4, vcc
	v_add_u32_e32 v4, 1, v1
	v_cmp_ge_u32_e32 vcc, v3, v2
	v_add_u32_e32 v3, 1, v5
	s_nop 0
	v_cndmask_b32_e32 v1, v1, v4, vcc
	v_mul_lo_u32 v4, v2, v1
	v_add_u32_e32 v2, v4, v2
	v_cmp_ne_u32_e32 vcc, v3, v2
	s_and_saveexec_b64 s[4:5], vcc
	s_xor_b64 s[4:5], exec, s[4:5]
	s_cbranch_execz .LBB0_443
	s_waitcnt lgkmcnt(0)
	v_mov_b32_e32 v0, 0x2000
	global_load_dword v0, v0, s[2:3] offset:1024 sc1
	s_add_u32 s46, s2, 0x2400
	s_addc_u32 s47, s3, 0
	s_waitcnt vmcnt(0)
	v_cmp_eq_u32_e32 vcc, v0, v1
	s_and_saveexec_b64 s[6:7], vcc
	s_cbranch_execz .LBB0_442
	s_add_u32 s40, s72, 0x80200
	s_addc_u32 s41, s73, 0
	s_mov_b32 s8, 1
	s_mov_b64 s[50:51], 0
	v_mov_b32_e32 v0, 0
	s_branch .LBB0_433

; __device__ __forceinline__ unsigned xb_ld(unsigned* p)              { return __hip_atomic_load(p, __ATOMIC_RELAXED, __HIP_MEMORY_SCOPE_AGENT); }
; __device__ __forceinline__ unsigned xb_add(unsigned* p, unsigned v) { return __hip_atomic_fetch_add(p, v, __ATOMIC_RELAXED, __HIP_MEMORY_SCOPE_AGENT); }
; #define XB_SPIN(cond, bar) do { unsigned _sp = 0; while (cond) { __builtin_amdgcn_s_sleep(1); \
;     if ((++_sp & 255u) == 0u) { if (xb_ld(&(bar)[XB_TMO])) break; if (_sp > XB_SPIN_CAP) { atomicAdd(&(bar)[XB_TMO], 1u); break; } } } } while (0)
; __device__ __forceinline__ void xcd_barrier(const XcdBarrier& b) {
;     asm volatile("s_waitcnt vmcnt(0)" ::: "memory");
;     __syncthreads();
;     if (threadIdx.x == 0) {
;         unsigned* bar = b.bar;
;         __builtin_amdgcn_s_waitcnt(0);
;         unsigned nloc = b.st[0], nx = b.st[1];
;         if (nloc == 0u) { xcd_barrier_complete(bar, b.x, nloc, nx); b.st[0] = nloc; b.st[1] = nx; }
;         const unsigned old = xb_add(&bar[XB_XSUB(b.x)], 1u);
;         const unsigned gen = old / nloc;
;         if (old + 1u == (gen + 1u) * nloc) {
;             __builtin_amdgcn_fence(__ATOMIC_RELEASE, "agent");
;             asm volatile("s_waitcnt vmcnt(0)" ::: "memory");
;             const unsigned og = xb_add(&bar[XB_TOP], 1u);
;             const unsigned tg = og / nx;
;             if (og + 1u == (tg + 1u) * nx) xb_add(&bar[XB_TOPGEN], 1u);
;             else XB_SPIN(xb_ld(&bar[XB_TOPGEN]) == tg, bar);
;             __builtin_amdgcn_fence(__ATOMIC_ACQUIRE, "agent");
;             xb_add(&bar[XB_XGEN(b.x)], 1u);
;             asm volatile("s_waitcnt vmcnt(0)" ::: "memory");
;         } else {
;             XB_SPIN(xb_ld(&bar[XB_XGEN(b.x)]) == gen, bar);
;             __builtin_amdgcn_fence(__ATOMIC_ACQUIRE, "agent");
.LBB0_540:
	s_or_b64 exec, exec, s[12:13]
	v_cvt_f32_u32_e32 v4, v2
	s_waitcnt vmcnt(0)
	v_readfirstlane_b32 s6, v3
	v_sub_u32_e32 v3, 0, v2
	v_rcp_iflag_f32_e32 v4, v4
	v_add_u32_e32 v5, s6, v1
	v_mul_u32_u24_e32 v250, 4, v2
	v_cmp_ne_u32_e64 s[12:13], v250, v5
	s_nop 3
	s_and_b64 s[12:13], s[12:13], exec
	s_cbranch_scc1 .Lfa_skip_4
	buffer_wbl2 sc1
.Lfa_skip_4:
	v_mul_f32_e32 v4, 0x4f7ffffe, v4
	v_cvt_u32_f32_e32 v4, v4
	v_mul_lo_u32 v1, v3, v4
	v_mul_hi_u32 v1, v4, v1
	v_add_u32_e32 v1, v4, v1
	v_mul_hi_u32 v1, v5, v1
	v_mul_lo_u32 v3, v1, v2
	v_sub_u32_e32 v3, v5, v3
	v_add_u32_e32 v4, 1, v1
	v_cmp_ge_u32_e32 vcc, v3, v2
	s_nop 1
	v_cndmask_b32_e32 v1, v1, v4, vcc
	v_sub_u32_e32 v4, v3, v2
	v_cndmask_b32_e32 v3, v3, v4, vcc
	v_add_u32_e32 v4, 1, v1
	v_cmp_ge_u32_e32 vcc, v3, v2
	v_add_u32_e32 v3, 1, v5
	s_nop 0
	v_cndmask_b32_e32 v1, v1, v4, vcc
	v_mul_lo_u32 v4, v2, v1
	v_add_u32_e32 v2, v4, v2
	v_cmp_ne_u32_e32 vcc, v3, v2
	s_and_saveexec_b64 s[6:7], vcc
	s_xor_b64 s[6:7], exec, s[6:7]
	s_cbranch_execz .LBB0_554
	s_waitcnt lgkmcnt(0)
	v_mov_b32_e32 v0, 0x2000
	global_load_dword v0, v0, s[4:5] offset:1024 sc1
	s_add_u32 s38, s4, 0x2400
	s_addc_u32 s39, s5, 0
	s_waitcnt vmcnt(0)
	v_cmp_eq_u32_e32 vcc, v0, v1
	s_and_saveexec_b64 s[12:13], vcc
	s_cbranch_execz .LBB0_553
	s_add_u32 s22, s72, 0x80200
	s_addc_u32 s23, s73, 0
	s_mov_b32 s8, 1
	s_mov_b64 s[42:43], 0
	v_mov_b32_e32 v0, 0
	s_branch .LBB0_544

; __device__ __forceinline__ unsigned xb_ld(unsigned* p)              { return __hip_atomic_load(p, __ATOMIC_RELAXED, __HIP_MEMORY_SCOPE_AGENT); }
; __device__ __forceinline__ unsigned xb_add(unsigned* p, unsigned v) { return __hip_atomic_fetch_add(p, v, __ATOMIC_RELAXED, __HIP_MEMORY_SCOPE_AGENT); }
; #define XB_SPIN(cond, bar) do { unsigned _sp = 0; while (cond) { __builtin_amdgcn_s_sleep(1); \
;     if ((++_sp & 255u) == 0u) { if (xb_ld(&(bar)[XB_TMO])) break; if (_sp > XB_SPIN_CAP) { atomicAdd(&(bar)[XB_TMO], 1u); break; } } } } while (0)
; __device__ __forceinline__ void xcd_barrier(const XcdBarrier& b) {
;     asm volatile("s_waitcnt vmcnt(0)" ::: "memory");
;     __syncthreads();
;     if (threadIdx.x == 0) {
;         unsigned* bar = b.bar;
;         __builtin_amdgcn_s_waitcnt(0);
;         unsigned nloc = b.st[0], nx = b.st[1];
;         if (nloc == 0u) { xcd_barrier_complete(bar, b.x, nloc, nx); b.st[0] = nloc; b.st[1] = nx; }
;         const unsigned old = xb_add(&bar[XB_XSUB(b.x)], 1u);
;         const unsigned gen = old / nloc;
;         if (old + 1u == (gen + 1u) * nloc) {
;             __builtin_amdgcn_fence(__ATOMIC_RELEASE, "agent");
;             asm volatile("s_waitcnt vmcnt(0)" ::: "memory");
;             const unsigned og = xb_add(&bar[XB_TOP], 1u);
;             const unsigned tg = og / nx;
;             if (og + 1u == (tg + 1u) * nx) xb_add(&bar[XB_TOPGEN], 1u);
;             else XB_SPIN(xb_ld(&bar[XB_TOPGEN]) == tg, bar);
;             __builtin_amdgcn_fence(__ATOMIC_ACQUIRE, "agent");
;             xb_add(&bar[XB_XGEN(b.x)], 1u);
;             asm volatile("s_waitcnt vmcnt(0)" ::: "memory");
;         } else {
;             XB_SPIN(xb_ld(&bar[XB_XGEN(b.x)]) == gen, bar);
;             __builtin_amdgcn_fence(__ATOMIC_ACQUIRE, "agent");
.LBB0_637:
	s_or_b64 exec, exec, s[12:13]
	v_cvt_f32_u32_e32 v4, v2
	s_waitcnt vmcnt(0)
	v_readfirstlane_b32 s6, v3
	v_sub_u32_e32 v3, 0, v2
	v_rcp_iflag_f32_e32 v4, v4
	v_add_u32_e32 v5, s6, v1
	v_mul_u32_u24_e32 v250, 5, v2
	v_cmp_ne_u32_e64 s[12:13], v250, v5
	s_nop 3
	s_and_b64 s[12:13], s[12:13], exec
	s_cbranch_scc1 .Lfa_skip_5
	buffer_wbl2 sc1
.Lfa_skip_5:
	v_mul_f32_e32 v4, 0x4f7ffffe, v4
	v_cvt_u32_f32_e32 v4, v4
	v_mul_lo_u32 v1, v3, v4
	v_mul_hi_u32 v1, v4, v1
	v_add_u32_e32 v1, v4, v1
	v_mul_hi_u32 v1, v5, v1
	v_mul_lo_u32 v3, v1, v2
	v_sub_u32_e32 v3, v5, v3
	v_add_u32_e32 v4, 1, v1
	v_cmp_ge_u32_e32 vcc, v3, v2
	s_nop 1
	v_cndmask_b32_e32 v1, v1, v4, vcc
	v_sub_u32_e32 v4, v3, v2
	v_cndmask_b32_e32 v3, v3, v4, vcc
	v_add_u32_e32 v4, 1, v1
	v_cmp_ge_u32_e32 vcc, v3, v2
	v_add_u32_e32 v3, 1, v5
	s_nop 0
	v_cndmask_b32_e32 v1, v1, v4, vcc
	v_mul_lo_u32 v4, v2, v1
	v_add_u32_e32 v2, v4, v2
	v_cmp_ne_u32_e32 vcc, v3, v2
	s_and_saveexec_b64 s[6:7], vcc
	s_xor_b64 s[6:7], exec, s[6:7]
	s_cbranch_execz .LBB0_651
	s_waitcnt lgkmcnt(0)
	v_mov_b32_e32 v0, 0x2000
	global_load_dword v0, v0, s[4:5] offset:1024 sc1
	s_add_u32 s40, s4, 0x2400
	s_addc_u32 s41, s5, 0
	s_waitcnt vmcnt(0)
	v_cmp_eq_u32_e32 vcc, v0, v1
	s_and_saveexec_b64 s[12:13], vcc
	s_cbranch_execz .LBB0_650
	s_add_u32 s22, s72, 0x80200
	s_addc_u32 s23, s73, 0
	s_mov_b32 s8, 1
	s_mov_b64 s[42:43], 0
	v_mov_b32_e32 v0, 0
	s_branch .LBB0_641

; __device__ __forceinline__ unsigned xb_add(unsigned* p, unsigned v) { return __hip_atomic_fetch_add(p, v, __ATOMIC_RELAXED, __HIP_MEMORY_SCOPE_AGENT); }
; __device__ __forceinline__ void xcd_barrier(const XcdBarrier& b) {
;     asm volatile("s_waitcnt vmcnt(0)" ::: "memory");
;     __syncthreads();
;     if (threadIdx.x == 0) {
;         unsigned* bar = b.bar;
;         __builtin_amdgcn_s_waitcnt(0);
;         unsigned nloc = b.st[0], nx = b.st[1];
;         if (nloc == 0u) { xcd_barrier_complete(bar, b.x, nloc, nx); b.st[0] = nloc; b.st[1] = nx; }
;         const unsigned old = xb_add(&bar[XB_XSUB(b.x)], 1u);
;         const unsigned gen = old / nloc;
;         if (old + 1u == (gen + 1u) * nloc) {
.LBB0_698:
	s_or_b64 exec, exec, s[12:13]
	v_cvt_f32_u32_e32 v4, v2
	s_waitcnt vmcnt(0)
	v_readfirstlane_b32 s6, v3
	v_sub_u32_e32 v3, 0, v2
	v_rcp_iflag_f32_e32 v4, v4
	v_add_u32_e32 v5, s6, v1
	v_mul_u32_u24_e32 v250, 6, v2
	v_cmp_ne_u32_e64 s[12:13], v250, v5
	s_nop 3
	s_and_b64 s[12:13], s[12:13], exec
	s_cbranch_scc1 .Lfa_skip_6
	buffer_wbl2 sc1

; __device__ __forceinline__ unsigned xb_ld(unsigned* p)              { return __hip_atomic_load(p, __ATOMIC_RELAXED, __HIP_MEMORY_SCOPE_AGENT); }
; __device__ __forceinline__ unsigned xb_add(unsigned* p, unsigned v) { return __hip_atomic_fetch_add(p, v, __ATOMIC_RELAXED, __HIP_MEMORY_SCOPE_AGENT); }
; #define XB_SPIN(cond, bar) do { unsigned _sp = 0; while (cond) { __builtin_amdgcn_s_sleep(1); \
;     if ((++_sp & 255u) == 0u) { if (xb_ld(&(bar)[XB_TMO])) break; if (_sp > XB_SPIN_CAP) { atomicAdd(&(bar)[XB_TMO], 1u); break; } } } } while (0)
; __device__ __forceinline__ void xcd_barrier(const XcdBarrier& b) {
;     asm volatile("s_waitcnt vmcnt(0)" ::: "memory");
;     __syncthreads();
;     if (threadIdx.x == 0) {
;         unsigned* bar = b.bar;
;         __builtin_amdgcn_s_waitcnt(0);
;         unsigned nloc = b.st[0], nx = b.st[1];
;         if (nloc == 0u) { xcd_barrier_complete(bar, b.x, nloc, nx); b.st[0] = nloc; b.st[1] = nx; }
;         const unsigned old = xb_add(&bar[XB_XSUB(b.x)], 1u);
;         const unsigned gen = old / nloc;
;         if (old + 1u == (gen + 1u) * nloc) {
;             __builtin_amdgcn_fence(__ATOMIC_RELEASE, "agent");
;             asm volatile("s_waitcnt vmcnt(0)" ::: "memory");
;             const unsigned og = xb_add(&bar[XB_TOP], 1u);
;             const unsigned tg = og / nx;
;             if (og + 1u == (tg + 1u) * nx) xb_add(&bar[XB_TOPGEN], 1u);
;             else XB_SPIN(xb_ld(&bar[XB_TOPGEN]) == tg, bar);
;             __builtin_amdgcn_fence(__ATOMIC_ACQUIRE, "agent");
;             xb_add(&bar[XB_XGEN(b.x)], 1u);
;             asm volatile("s_waitcnt vmcnt(0)" ::: "memory");
;         } else {
;             XB_SPIN(xb_ld(&bar[XB_XGEN(b.x)]) == gen, bar);
;             __builtin_amdgcn_fence(__ATOMIC_ACQUIRE, "agent");
.LBB0_811:
	s_or_b64 exec, exec, s[24:25]
	v_cvt_f32_u32_e32 v4, v2
	s_waitcnt vmcnt(0)
	v_readfirstlane_b32 s6, v3
	v_sub_u32_e32 v3, 0, v2
	v_rcp_iflag_f32_e32 v4, v4
	v_add_u32_e32 v5, s6, v1
	v_mul_u32_u24_e32 v250, 7, v2
	v_cmp_ne_u32_e64 s[24:25], v250, v5
	s_nop 3
	s_and_b64 s[24:25], s[24:25], exec
	s_cbranch_scc1 .Lfa_skip_7
	buffer_wbl2 sc1
.Lfa_skip_7:
	v_mul_f32_e32 v4, 0x4f7ffffe, v4
	v_cvt_u32_f32_e32 v4, v4
	v_mul_lo_u32 v1, v3, v4
	v_mul_hi_u32 v1, v4, v1
	v_add_u32_e32 v1, v4, v1
	v_mul_hi_u32 v1, v5, v1
	v_mul_lo_u32 v3, v1, v2
	v_sub_u32_e32 v3, v5, v3
	v_add_u32_e32 v4, 1, v1
	v_cmp_ge_u32_e32 vcc, v3, v2
	s_nop 1
	v_cndmask_b32_e32 v1, v1, v4, vcc
	v_sub_u32_e32 v4, v3, v2
	v_cndmask_b32_e32 v3, v3, v4, vcc
	v_add_u32_e32 v4, 1, v1
	v_cmp_ge_u32_e32 vcc, v3, v2
	v_add_u32_e32 v3, 1, v5
	s_nop 0
	v_cndmask_b32_e32 v1, v1, v4, vcc
	v_mul_lo_u32 v4, v2, v1
	v_add_u32_e32 v2, v4, v2
	v_cmp_ne_u32_e32 vcc, v3, v2
	s_and_saveexec_b64 s[6:7], vcc
	s_xor_b64 s[6:7], exec, s[6:7]
	s_cbranch_execz .LBB0_825
	s_waitcnt lgkmcnt(0)
	v_mov_b32_e32 v0, 0x2000
	global_load_dword v0, v0, s[4:5] offset:1024 sc1
	s_add_u32 s38, s4, 0x2400
	s_addc_u32 s39, s5, 0
	s_waitcnt vmcnt(0)
	v_cmp_eq_u32_e32 vcc, v0, v1
	s_and_saveexec_b64 s[24:25], vcc
	s_cbranch_execz .LBB0_824
	s_add_u32 s26, s72, 0x80200
	s_addc_u32 s27, s73, 0
	s_mov_b32 s8, 1
	s_mov_b64 s[40:41], 0
	v_mov_b32_e32 v0, 0
	s_branch .LBB0_815

; __device__ __forceinline__ unsigned xb_ld(unsigned* p)              { return __hip_atomic_load(p, __ATOMIC_RELAXED, __HIP_MEMORY_SCOPE_AGENT); }
; __device__ __forceinline__ unsigned xb_add(unsigned* p, unsigned v) { return __hip_atomic_fetch_add(p, v, __ATOMIC_RELAXED, __HIP_MEMORY_SCOPE_AGENT); }
; #define XB_SPIN(cond, bar) do { unsigned _sp = 0; while (cond) { __builtin_amdgcn_s_sleep(1); \
;     if ((++_sp & 255u) == 0u) { if (xb_ld(&(bar)[XB_TMO])) break; if (_sp > XB_SPIN_CAP) { atomicAdd(&(bar)[XB_TMO], 1u); break; } } } } while (0)
; __device__ __forceinline__ void xcd_barrier(const XcdBarrier& b) {
;     asm volatile("s_waitcnt vmcnt(0)" ::: "memory");
;     __syncthreads();
;     if (threadIdx.x == 0) {
;         unsigned* bar = b.bar;
;         __builtin_amdgcn_s_waitcnt(0);
;         unsigned nloc = b.st[0], nx = b.st[1];
;         if (nloc == 0u) { xcd_barrier_complete(bar, b.x, nloc, nx); b.st[0] = nloc; b.st[1] = nx; }
;         const unsigned old = xb_add(&bar[XB_XSUB(b.x)], 1u);
;         const unsigned gen = old / nloc;
;         if (old + 1u == (gen + 1u) * nloc) {
;             __builtin_amdgcn_fence(__ATOMIC_RELEASE, "agent");
;             asm volatile("s_waitcnt vmcnt(0)" ::: "memory");
;             const unsigned og = xb_add(&bar[XB_TOP], 1u);
;             const unsigned tg = og / nx;
;             if (og + 1u == (tg + 1u) * nx) xb_add(&bar[XB_TOPGEN], 1u);
;             else XB_SPIN(xb_ld(&bar[XB_TOPGEN]) == tg, bar);
;             __builtin_amdgcn_fence(__ATOMIC_ACQUIRE, "agent");
;             xb_add(&bar[XB_XGEN(b.x)], 1u);
;             asm volatile("s_waitcnt vmcnt(0)" ::: "memory");
;         } else {
;             XB_SPIN(xb_ld(&bar[XB_XGEN(b.x)]) == gen, bar);
;             __builtin_amdgcn_fence(__ATOMIC_ACQUIRE, "agent");
.LBB0_1029:
	s_or_b64 exec, exec, s[14:15]
	v_cvt_f32_u32_e32 v4, v2
	s_waitcnt vmcnt(0)
	v_readfirstlane_b32 s6, v3
	v_sub_u32_e32 v3, 0, v2
	v_rcp_iflag_f32_e32 v4, v4
	v_add_u32_e32 v5, s6, v1
	v_mul_u32_u24_e32 v250, 8, v2
	v_cmp_ne_u32_e64 s[14:15], v250, v5
	s_nop 3
	s_and_b64 s[14:15], s[14:15], exec
	s_cbranch_scc1 .Lfa_skip_8
	buffer_wbl2 sc1
.Lfa_skip_8:
	v_mul_f32_e32 v4, 0x4f7ffffe, v4
	v_cvt_u32_f32_e32 v4, v4
	v_mul_lo_u32 v1, v3, v4
	v_mul_hi_u32 v1, v4, v1
	v_add_u32_e32 v1, v4, v1
	v_mul_hi_u32 v1, v5, v1
	v_mul_lo_u32 v3, v1, v2
	v_sub_u32_e32 v3, v5, v3
	v_add_u32_e32 v4, 1, v1
	v_cmp_ge_u32_e32 vcc, v3, v2
	s_nop 1
	v_cndmask_b32_e32 v1, v1, v4, vcc
	v_sub_u32_e32 v4, v3, v2
	v_cndmask_b32_e32 v3, v3, v4, vcc
	v_add_u32_e32 v4, 1, v1
	v_cmp_ge_u32_e32 vcc, v3, v2
	v_add_u32_e32 v3, 1, v5
	s_nop 0
	v_cndmask_b32_e32 v1, v1, v4, vcc
	v_mul_lo_u32 v4, v2, v1
	v_add_u32_e32 v2, v4, v2
	v_cmp_ne_u32_e32 vcc, v3, v2
	s_and_saveexec_b64 s[6:7], vcc
	s_xor_b64 s[6:7], exec, s[6:7]
	s_cbranch_execz .LBB0_1043
	s_waitcnt lgkmcnt(0)
	v_mov_b32_e32 v0, 0x2000
	global_load_dword v0, v0, s[4:5] offset:1024 sc1
	s_add_u32 s18, s4, 0x2400
	s_addc_u32 s19, s5, 0
	s_waitcnt vmcnt(0)
	v_cmp_eq_u32_e32 vcc, v0, v1
	s_and_saveexec_b64 s[14:15], vcc
	s_cbranch_execz .LBB0_1042
	s_add_u32 s16, s72, 0x80200
	s_addc_u32 s17, s73, 0
	s_mov_b32 s8, 1
	s_mov_b64 s[20:21], 0
	v_mov_b32_e32 v0, 0
	s_branch .LBB0_1033

; __device__ __forceinline__ unsigned xb_ld(unsigned* p)              { return __hip_atomic_load(p, __ATOMIC_RELAXED, __HIP_MEMORY_SCOPE_AGENT); }
; __device__ __forceinline__ unsigned xb_add(unsigned* p, unsigned v) { return __hip_atomic_fetch_add(p, v, __ATOMIC_RELAXED, __HIP_MEMORY_SCOPE_AGENT); }
; #define XB_SPIN(cond, bar) do { unsigned _sp = 0; while (cond) { __builtin_amdgcn_s_sleep(1); \
;     if ((++_sp & 255u) == 0u) { if (xb_ld(&(bar)[XB_TMO])) break; if (_sp > XB_SPIN_CAP) { atomicAdd(&(bar)[XB_TMO], 1u); break; } } } } while (0)
; __device__ __forceinline__ void xcd_barrier(const XcdBarrier& b) {
;     asm volatile("s_waitcnt vmcnt(0)" ::: "memory");
;     __syncthreads();
;     if (threadIdx.x == 0) {
;         unsigned* bar = b.bar;
;         __builtin_amdgcn_s_waitcnt(0);
;         unsigned nloc = b.st[0], nx = b.st[1];
;         if (nloc == 0u) { xcd_barrier_complete(bar, b.x, nloc, nx); b.st[0] = nloc; b.st[1] = nx; }
;         const unsigned old = xb_add(&bar[XB_XSUB(b.x)], 1u);
;         const unsigned gen = old / nloc;
;         if (old + 1u == (gen + 1u) * nloc) {
;             __builtin_amdgcn_fence(__ATOMIC_RELEASE, "agent");
;             asm volatile("s_waitcnt vmcnt(0)" ::: "memory");
;             const unsigned og = xb_add(&bar[XB_TOP], 1u);
;             const unsigned tg = og / nx;
;             if (og + 1u == (tg + 1u) * nx) xb_add(&bar[XB_TOPGEN], 1u);
;             else XB_SPIN(xb_ld(&bar[XB_TOPGEN]) == tg, bar);
;             __builtin_amdgcn_fence(__ATOMIC_ACQUIRE, "agent");
;             xb_add(&bar[XB_XGEN(b.x)], 1u);
;             asm volatile("s_waitcnt vmcnt(0)" ::: "memory");
;         } else {
;             XB_SPIN(xb_ld(&bar[XB_XGEN(b.x)]) == gen, bar);
;             __builtin_amdgcn_fence(__ATOMIC_ACQUIRE, "agent");
.LBB0_1126:
	s_or_b64 exec, exec, s[14:15]
	v_cvt_f32_u32_e32 v4, v2
	s_waitcnt vmcnt(0)
	v_readfirstlane_b32 s6, v3
	v_sub_u32_e32 v3, 0, v2
	v_rcp_iflag_f32_e32 v4, v4
	v_add_u32_e32 v5, s6, v1
	v_mul_u32_u24_e32 v250, 9, v2
	v_cmp_ne_u32_e64 s[14:15], v250, v5
	s_nop 3
	s_and_b64 s[14:15], s[14:15], exec
	s_cbranch_scc1 .Lfa_skip_9
	buffer_wbl2 sc1
.Lfa_skip_9:
	v_mul_f32_e32 v4, 0x4f7ffffe, v4
	v_cvt_u32_f32_e32 v4, v4
	v_mul_lo_u32 v1, v3, v4
	v_mul_hi_u32 v1, v4, v1
	v_add_u32_e32 v1, v4, v1
	v_mul_hi_u32 v1, v5, v1
	v_mul_lo_u32 v3, v1, v2
	v_sub_u32_e32 v3, v5, v3
	v_add_u32_e32 v4, 1, v1
	v_cmp_ge_u32_e32 vcc, v3, v2
	s_nop 1
	v_cndmask_b32_e32 v1, v1, v4, vcc
	v_sub_u32_e32 v4, v3, v2
	v_cndmask_b32_e32 v3, v3, v4, vcc
	v_add_u32_e32 v4, 1, v1
	v_cmp_ge_u32_e32 vcc, v3, v2
	v_add_u32_e32 v3, 1, v5
	s_nop 0
	v_cndmask_b32_e32 v1, v1, v4, vcc
	v_mul_lo_u32 v4, v2, v1
	v_add_u32_e32 v2, v4, v2
	v_cmp_ne_u32_e32 vcc, v3, v2
	s_and_saveexec_b64 s[6:7], vcc
	s_xor_b64 s[6:7], exec, s[6:7]
	s_cbranch_execz .LBB0_1140
	s_waitcnt lgkmcnt(0)
	v_mov_b32_e32 v0, 0x2000
	global_load_dword v0, v0, s[2:3] offset:1024 sc1
	s_add_u32 s18, s2, 0x2400
	s_addc_u32 s19, s3, 0
	s_waitcnt vmcnt(0)
	v_cmp_eq_u32_e32 vcc, v0, v1
	s_and_saveexec_b64 s[14:15], vcc
	s_cbranch_execz .LBB0_1139
	s_add_u32 s16, s72, 0x80200
	s_addc_u32 s17, s73, 0
	s_mov_b32 s8, 1
	s_mov_b64 s[20:21], 0
	v_mov_b32_e32 v0, 0
	s_branch .LBB0_1130

; __device__ __forceinline__ unsigned xb_add(unsigned* p, unsigned v) { return __hip_atomic_fetch_add(p, v, __ATOMIC_RELAXED, __HIP_MEMORY_SCOPE_AGENT); }
; __device__ __forceinline__ void xcd_barrier(const XcdBarrier& b) {
;     asm volatile("s_waitcnt vmcnt(0)" ::: "memory");
;     __syncthreads();
;     if (threadIdx.x == 0) {
;         unsigned* bar = b.bar;
;         __builtin_amdgcn_s_waitcnt(0);
;         unsigned nloc = b.st[0], nx = b.st[1];
;         if (nloc == 0u) { xcd_barrier_complete(bar, b.x, nloc, nx); b.st[0] = nloc; b.st[1] = nx; }
;         const unsigned old = xb_add(&bar[XB_XSUB(b.x)], 1u);
;         const unsigned gen = old / nloc;
;         if (old + 1u == (gen + 1u) * nloc) {
.LBB0_1252:
	s_or_b64 exec, exec, s[14:15]
	v_cvt_f32_u32_e32 v4, v2
	s_waitcnt vmcnt(0)
	v_readfirstlane_b32 s6, v3
	v_sub_u32_e32 v3, 0, v2
	v_rcp_iflag_f32_e32 v4, v4
	v_add_u32_e32 v5, s6, v1
	v_mul_u32_u24_e32 v250, 10, v2
	v_cmp_ne_u32_e64 s[14:15], v250, v5
	s_nop 3
	s_and_b64 s[14:15], s[14:15], exec
	s_cbranch_scc1 .Lfa_skip_10
	buffer_wbl2 sc1

; __device__ __forceinline__ unsigned xb_ld(unsigned* p)              { return __hip_atomic_load(p, __ATOMIC_RELAXED, __HIP_MEMORY_SCOPE_AGENT); }
; __device__ __forceinline__ unsigned xb_add(unsigned* p, unsigned v) { return __hip_atomic_fetch_add(p, v, __ATOMIC_RELAXED, __HIP_MEMORY_SCOPE_AGENT); }
; #define XB_SPIN(cond, bar) do { unsigned _sp = 0; while (cond) { __builtin_amdgcn_s_sleep(1); \
;     if ((++_sp & 255u) == 0u) { if (xb_ld(&(bar)[XB_TMO])) break; if (_sp > XB_SPIN_CAP) { atomicAdd(&(bar)[XB_TMO], 1u); break; } } } } while (0)
; __device__ __forceinline__ void xcd_barrier(const XcdBarrier& b) {
;     asm volatile("s_waitcnt vmcnt(0)" ::: "memory");
;     __syncthreads();
;     if (threadIdx.x == 0) {
;         unsigned* bar = b.bar;
;         __builtin_amdgcn_s_waitcnt(0);
;         unsigned nloc = b.st[0], nx = b.st[1];
;         if (nloc == 0u) { xcd_barrier_complete(bar, b.x, nloc, nx); b.st[0] = nloc; b.st[1] = nx; }
;         const unsigned old = xb_add(&bar[XB_XSUB(b.x)], 1u);
;         const unsigned gen = old / nloc;
;         if (old + 1u == (gen + 1u) * nloc) {
;             __builtin_amdgcn_fence(__ATOMIC_RELEASE, "agent");
;             asm volatile("s_waitcnt vmcnt(0)" ::: "memory");
;             const unsigned og = xb_add(&bar[XB_TOP], 1u);
;             const unsigned tg = og / nx;
;             if (og + 1u == (tg + 1u) * nx) xb_add(&bar[XB_TOPGEN], 1u);
;             else XB_SPIN(xb_ld(&bar[XB_TOPGEN]) == tg, bar);
;             __builtin_amdgcn_fence(__ATOMIC_ACQUIRE, "agent");
;             xb_add(&bar[XB_XGEN(b.x)], 1u);
;             asm volatile("s_waitcnt vmcnt(0)" ::: "memory");
;         } else {
;             XB_SPIN(xb_ld(&bar[XB_XGEN(b.x)]) == gen, bar);
;             __builtin_amdgcn_fence(__ATOMIC_ACQUIRE, "agent");
.LBB0_1349:
	s_or_b64 exec, exec, s[12:13]
	v_cvt_f32_u32_e32 v4, v2
	s_waitcnt vmcnt(0)
	v_readfirstlane_b32 s6, v3
	v_sub_u32_e32 v3, 0, v2
	v_rcp_iflag_f32_e32 v4, v4
	v_add_u32_e32 v5, s6, v1
	v_mul_u32_u24_e32 v250, 11, v2
	v_cmp_ne_u32_e64 s[12:13], v250, v5
	s_nop 3
	s_and_b64 s[12:13], s[12:13], exec
	s_cbranch_scc1 .Lfa_skip_11
	buffer_wbl2 sc1
.Lfa_skip_11:
	v_mul_f32_e32 v4, 0x4f7ffffe, v4
	v_cvt_u32_f32_e32 v4, v4
	v_mul_lo_u32 v1, v3, v4
	v_mul_hi_u32 v1, v4, v1
	v_add_u32_e32 v1, v4, v1
	v_mul_hi_u32 v1, v5, v1
	v_mul_lo_u32 v3, v1, v2
	v_sub_u32_e32 v3, v5, v3
	v_add_u32_e32 v4, 1, v1
	v_cmp_ge_u32_e32 vcc, v3, v2
	s_nop 1
	v_cndmask_b32_e32 v1, v1, v4, vcc
	v_sub_u32_e32 v4, v3, v2
	v_cndmask_b32_e32 v3, v3, v4, vcc
	v_add_u32_e32 v4, 1, v1
	v_cmp_ge_u32_e32 vcc, v3, v2
	v_add_u32_e32 v3, 1, v5
	s_nop 0
	v_cndmask_b32_e32 v1, v1, v4, vcc
	v_mul_lo_u32 v4, v2, v1
	v_add_u32_e32 v2, v4, v2
	v_cmp_ne_u32_e32 vcc, v3, v2
	s_and_saveexec_b64 s[6:7], vcc
	s_xor_b64 s[6:7], exec, s[6:7]
	s_cbranch_execz .LBB0_1363
	s_waitcnt lgkmcnt(0)
	v_mov_b32_e32 v0, 0x2000
	global_load_dword v0, v0, s[4:5] offset:1024 sc1
	s_add_u32 s16, s4, 0x2400
	s_addc_u32 s17, s5, 0
	s_waitcnt vmcnt(0)
	v_cmp_eq_u32_e32 vcc, v0, v1
	s_and_saveexec_b64 s[12:13], vcc
	s_cbranch_execz .LBB0_1362
	s_add_u32 s14, s72, 0x80200
	s_addc_u32 s15, s73, 0
	s_mov_b32 s8, 1
	s_mov_b64 s[18:19], 0
	v_mov_b32_e32 v0, 0
	s_branch .LBB0_1353
